# v11 + idle seam waves also touch the first A-panel K-tiles of the next GEMM phase
# baseline (speedup 1.0000x reference)
;     __host__ __device__ bool next(int i, Unit& u) const {
;         const int L = i * G + c; if (L >= nwg) return false;
;         const int nig = WGM * nN, gid = L / nig, fm = gid * WGM, gsz = (nM - fm) < WGM ? (nM - fm) : WGM;
;         u.pm = fm + ((L % nig) % gsz); u.pn = (L % nig) / gsz; return true;
; template <int L>
; __device__ __forceinline__ void layer(const Args& a, LAS unsigned char* lds, const XcdBarrier& bar, int lo, int hi, int wave, int lane, int b, int r, int GS) {
;     ...
;         pg8::Gemm g{HB, (const bf16*)(wl + W2_OFF), SEQ, D, DFF}; pg8::GroupOrder S; S.init(SEQ, D, GS, r);
;         pg8::EpiResid E{nullptr, XN, rowss + (size_t)(3 * L + 1) * M, 0.5f, D};
;         pg8::gemm_phase<pg8::EpiResid, pg8::GroupOrder, true, true>(lds, g, S, E);
.Lbpf_skip_0:
	s_cmp_eq_u32 s97, 0
	s_cbranch_scc1 .Lapf_skip_0
	v_readlane_b32 s101, v230, 6
	s_nop 3
	s_mul_i32 s101, s101, 704
	s_add_u32 s101, s101, 0xa000000
	v_mov_b32_e32 v233, s97
	v_add_u32_e32 v233, -1, v233
	v_lshl_add_u32 v233, v233, 6, v200
	v_mov_b32_e32 v234, s95
	v_lshrrev_b32_e32 v235, 4, v234
	v_and_b32_e32 v234, 3, v234
	v_lshl_or_b32 v234, v235, 2, v234
	v_lshlrev_b32_e32 v234, 8, v234
	v_lshrrev_b32_e32 v235, 1, v233
	v_add_u32_e32 v234, v234, v235
	v_mul_u32_u24_e32 v234, 0x1600, v234
	v_and_b32_e32 v233, 1, v233
	v_lshlrev_b32_e32 v233, 7, v233
	v_add3_u32 v233, v234, v233, s101
	global_load_dword v231, v233, s[34:35]

;     __host__ __device__ bool next(int i, Unit& u) const {
;         const int L = i * G + c; if (L >= nwg) return false;
;         const int nig = WGM * nN, gid = L / nig, fm = gid * WGM, gsz = (nM - fm) < WGM ? (nM - fm) : WGM;
;         u.pm = fm + ((L % nig) % gsz); u.pn = (L % nig) / gsz; return true;
; template <int L>
; __device__ __forceinline__ void layer(const Args& a, LAS unsigned char* lds, const XcdBarrier& bar, int lo, int hi, int wave, int lane, int b, int r, int GS) {
;     ...
;         pg8::Gemm g{XN, (const bf16*)(wl + WIN_OFF), SEQ, 2560, D}; pg8::GroupOrder S; S.init(SEQ, 2560, GS, r);
;         pg8::EpiProj E{HB, NPROJ, rowss + (size_t)(3 * L + 1) * M, rowss + (size_t)(7 + L) * M, RB, 1.f / D, EPS};
;         pg8::gemm_phase<pg8::EpiProj, pg8::GroupOrder, true, true>(lds, g, S, E);
.Lbpf_skip_1:
	s_cmp_eq_u32 s97, 0
	s_cbranch_scc1 .Lapf_skip_1
	v_readlane_b32 s101, v230, 6
	s_nop 3
	s_mul_i32 s101, s101, 256
	s_add_u32 s101, s101, 0x6000000
	v_mov_b32_e32 v233, s97
	v_add_u32_e32 v233, -1, v233
	v_lshl_add_u32 v233, v233, 6, v200
	v_mov_b32_e32 v234, s95
	v_and_b32_e32 v234, 3, v234
	v_lshlrev_b32_e32 v234, 8, v234
	v_lshrrev_b32_e32 v235, 1, v233
	v_add_u32_e32 v234, v234, v235
	v_mul_u32_u24_e32 v234, 0x800, v234
	v_and_b32_e32 v233, 1, v233
	v_lshlrev_b32_e32 v233, 7, v233
	v_add3_u32 v233, v234, v233, s101
	global_load_dword v231, v233, s[34:35]

;     __host__ __device__ bool next(int i, Unit& u) const {
;         const int L = i * G + c; if (L >= nwg) return false;
;         const int nig = WGM * nN, gid = L / nig, fm = gid * WGM, gsz = (nM - fm) < WGM ? (nM - fm) : WGM;
;         u.pm = fm + ((L % nig) % gsz); u.pn = (L % nig) / gsz; return true;
; template <int L>
; __device__ __forceinline__ void layer(const Args& a, LAS unsigned char* lds, const XcdBarrier& bar, int lo, int hi, int wave, int lane, int b, int r, int GS) {
;     ...
;         pg8::Gemm g{YB, (const bf16*)(wl + WOUT_OFF), SEQ, D, D}; pg8::GroupOrder S; S.init(SEQ, D, GS, r);
;         pg8::EpiResid E{nullptr, XN, rowss + (size_t)(3 * L + 2) * M, 1.0f, D};
;         pg8::gemm_phase<pg8::EpiResid, pg8::GroupOrder, true, true>(lds, g, S, E);
.Lbpf_skip_5:
	s_cmp_eq_u32 s97, 0
	s_cbranch_scc1 .Lapf_skip_5
	v_readlane_b32 s101, v230, 6
	s_nop 3
	s_mul_i32 s101, s101, 256
	s_add_u32 s101, s101, 0x15000000
	v_mov_b32_e32 v233, s97
	v_add_u32_e32 v233, -1, v233
	v_lshl_add_u32 v233, v233, 6, v200
	v_mov_b32_e32 v234, s95
	v_lshrrev_b32_e32 v235, 4, v234
	v_and_b32_e32 v234, 3, v234
	v_lshl_or_b32 v234, v235, 2, v234
	v_lshlrev_b32_e32 v234, 8, v234
	v_lshrrev_b32_e32 v235, 1, v233
	v_add_u32_e32 v234, v234, v235
	v_mul_u32_u24_e32 v234, 0x800, v234
	v_and_b32_e32 v233, 1, v233
	v_lshlrev_b32_e32 v233, 7, v233
	v_add3_u32 v233, v234, v233, s101
	global_load_dword v231, v233, s[34:35]
